# attention MFMA halves: one LDS-fragment wait per two MFMAs instead of one per MFMA (fewer issue slots in the MFMA stream)
# baseline (speedup 1.0000x reference)
.Latt_b_bar:
	s_waitcnt lgkmcnt(0)
	s_barrier
	s_cmp_gt_i32 s86, s9
	s_cbranch_scc1 .LBB0_241
	s_cmp_ge_i32 s86, s9
	s_cbranch_scc1 .Latt_b_pvonly
	s_mul_i32 s4, s69, 0x5000
	v_add_u32_e32 v205, s4, v165
	v_add_u32_e32 v206, s28, v192
	ds_read_b64_tr_b16 v[96:97], v205 offset:34816
	ds_read_b64_tr_b16 v[98:99], v205 offset:37376
	ds_read_b64_tr_b16 v[100:101], v205 offset:39936
	ds_read_b64_tr_b16 v[102:103], v205 offset:42496
	ds_read_b64_tr_b16 v[104:105], v205 offset:45056
	ds_read_b64_tr_b16 v[106:107], v205 offset:47616
	ds_read_b64_tr_b16 v[108:109], v205 offset:50176
	ds_read_b64_tr_b16 v[110:111], v205 offset:52736
	ds_read_b64_tr_b16 v[176:177], v205 offset:34880
	ds_read_b64_tr_b16 v[178:179], v205 offset:37440
	ds_read_b64_tr_b16 v[180:181], v205 offset:40000
	ds_read_b64_tr_b16 v[182:183], v205 offset:42560
	ds_read_b64_tr_b16 v[184:185], v205 offset:45120
	ds_read_b64_tr_b16 v[186:187], v205 offset:47680
	s_setprio 1
	s_waitcnt lgkmcnt(10)
	v_mfma_f32_32x32x16_bf16 v[32:47], v[96:99], v[80:83], v[32:47]
	ds_read_b64_tr_b16 v[96:97], v205 offset:50240
	ds_read_b64_tr_b16 v[98:99], v205 offset:52800
	v_mfma_f32_32x32x16_bf16 v[32:47], v[100:103], v[84:87], v[32:47]
	ds_read_b64_tr_b16 v[100:101], v205 offset:34944
	ds_read_b64_tr_b16 v[102:103], v205 offset:37504
	s_waitcnt lgkmcnt(10)
	v_mfma_f32_32x32x16_bf16 v[32:47], v[104:107], v[88:91], v[32:47]
	ds_read_b64_tr_b16 v[104:105], v205 offset:40064
	ds_read_b64_tr_b16 v[106:107], v205 offset:42624
	v_mfma_f32_32x32x16_bf16 v[32:47], v[108:111], v[92:95], v[32:47]
	ds_read_b64_tr_b16 v[108:109], v205 offset:45184
	ds_read_b64_tr_b16 v[110:111], v205 offset:47744
	s_waitcnt lgkmcnt(10)
	v_mfma_f32_32x32x16_bf16 v[16:31], v[176:179], v[80:83], v[16:31]
	ds_read_b64_tr_b16 v[176:177], v205 offset:50304
	ds_read_b64_tr_b16 v[178:179], v205 offset:52864
	v_mfma_f32_32x32x16_bf16 v[16:31], v[180:183], v[84:87], v[16:31]
	ds_read_b64_tr_b16 v[180:181], v205 offset:35008
	ds_read_b64_tr_b16 v[182:183], v205 offset:37568
	s_waitcnt lgkmcnt(10)
	v_mfma_f32_32x32x16_bf16 v[16:31], v[184:187], v[88:91], v[16:31]
	ds_read_b64_tr_b16 v[184:185], v205 offset:40128
	ds_read_b64_tr_b16 v[186:187], v205 offset:42688
	v_mfma_f32_32x32x16_bf16 v[16:31], v[96:99], v[92:95], v[16:31]
	ds_read_b64_tr_b16 v[96:97], v205 offset:45248
	ds_read_b64_tr_b16 v[98:99], v205 offset:47808
	s_waitcnt lgkmcnt(10)
	v_mfma_f32_32x32x16_bf16 v[0:15], v[100:103], v[80:83], v[0:15]
	ds_read_b64_tr_b16 v[100:101], v205 offset:50368
	ds_read_b64_tr_b16 v[102:103], v205 offset:52928
	v_mfma_f32_32x32x16_bf16 v[0:15], v[104:107], v[84:87], v[0:15]
	ds_read_b128 v[210:213], v206 offset:8704
	ds_read_b128 v[104:107], v206 offset:8736
	s_waitcnt lgkmcnt(10)
	v_mfma_f32_32x32x16_bf16 v[0:15], v[108:111], v[88:91], v[0:15]
	ds_read_b128 v[108:111], v206 offset:8768
	ds_read_b128 v[188:191], v206
	v_mfma_f32_32x32x16_bf16 v[0:15], v[176:179], v[92:95], v[0:15]
	ds_read_b128 v[176:179], v206 offset:8800
	ds_read_b128 v[224:227], v206 offset:32
	s_waitcnt lgkmcnt(10)
	v_mfma_f32_32x32x16_bf16 v[48:63], v[180:183], v[80:83], v[48:63]
	ds_read_b128 v[228:231], v206 offset:64
	ds_read_b128 v[248:251], v206 offset:96
	v_mfma_f32_32x32x16_bf16 v[48:63], v[184:187], v[84:87], v[48:63]
	s_waitcnt lgkmcnt(8)
	v_mfma_f32_32x32x16_bf16 v[48:63], v[96:99], v[88:91], v[48:63]
	v_mfma_f32_32x32x16_bf16 v[48:63], v[100:103], v[92:95], v[48:63]
	s_waitcnt lgkmcnt(6)
	v_mfma_f32_32x32x16_bf16 v[80:95], v[210:213], v[112:115], v[64:79]
	v_mfma_f32_32x32x16_bf16 v[80:95], v[104:107], v[116:119], v[80:95]
	s_waitcnt lgkmcnt(3)
	v_mfma_f32_32x32x16_bf16 v[80:95], v[108:111], v[120:123], v[80:95]
	v_mfma_f32_32x32x16_bf16 v[80:95], v[176:179], v[124:127], v[80:95]
	s_waitcnt lgkmcnt(2)
	v_mfma_f32_32x32x16_bf16 v[96:111], v[188:191], v[112:115], v[64:79]
	v_mfma_f32_32x32x16_bf16 v[96:111], v[224:227], v[116:119], v[96:111]
	s_waitcnt lgkmcnt(0)
	v_mfma_f32_32x32x16_bf16 v[96:111], v[228:231], v[120:123], v[96:111]
	v_mfma_f32_32x32x16_bf16 v[96:111], v[248:251], v[124:127], v[96:111]
	s_setprio 0
	s_cmp_gt_i32 s33, 3
	s_cbranch_scc1 .Latt_b_stg
	s_waitcnt lgkmcnt(0)
	s_add_i32 s4, s68, 0x100
	v_add_u32_e32 v205, s4, v204
	v_add_u32_e32 v176, 0x17d00, v205
	v_add_u32_e32 v178, 0x17d80, v205
	ds_read2_b32 v[176:177], v176 offset1:1
	ds_read2_b32 v[178:179], v178 offset1:1
	v_add_u32_e32 v180, 0x17d08, v205
	v_add_u32_e32 v182, 0x17d88, v205
	v_add_u32_e32 v184, 0x17d20, v205
	v_add_u32_e32 v186, 0x17da0, v205
	v_add_u32_e32 v188, 0x17d28, v205
	v_add_u32_e32 v190, 0x17da8, v205
	v_add_u32_e32 v206, 0x17d40, v205
	v_add_u32_e32 v210, 0x17dc0, v205
	v_add_u32_e32 v212, 0x17d48, v205
	v_add_u32_e32 v221, 0x17dc8, v205
	ds_read2_b32 v[180:181], v180 offset1:1
	ds_read2_b32 v[182:183], v182 offset1:1
	ds_read2_b32 v[184:185], v184 offset1:1
	ds_read2_b32 v[186:187], v186 offset1:1
	ds_read2_b32 v[188:189], v188 offset1:1
	ds_read2_b32 v[190:191], v190 offset1:1
	ds_read2_b32 v[206:207], v206 offset1:1
	ds_read2_b32 v[210:211], v210 offset1:1
	ds_read2_b32 v[212:213], v212 offset1:1
	ds_read2_b32 v[224:225], v221 offset1:1
	v_add_u32_e32 v221, 0x17d60, v205
	v_add_u32_e32 v223, 0x17de0, v205
	ds_read2_b32 v[226:227], v221 offset1:1
	ds_read2_b32 v[228:229], v223 offset1:1
	v_add_u32_e32 v221, 0x17d68, v205
	v_add_u32_e32 v205, 0x17de8, v205
	ds_read2_b32 v[230:231], v221 offset1:1
	s_waitcnt lgkmcnt(14)
	v_pk_add_f32 v[96:97], v[96:97], v[176:177]
	ds_read2_b32 v[176:177], v205 offset1:1
	s_waitcnt lgkmcnt(3)
	v_pk_add_f32 v[108:109], v[108:109], v[226:227]
	v_pk_add_f32 v[106:107], v[106:107], v[212:213]
	s_waitcnt lgkmcnt(1)
	v_pk_add_f32 v[110:111], v[110:111], v[230:231]
	v_pk_add_f32 v[104:105], v[104:105], v[206:207]
	v_pk_add_f32 v[102:103], v[102:103], v[188:189]
	v_pk_add_f32 v[100:101], v[100:101], v[184:185]
	v_pk_add_f32 v[98:99], v[98:99], v[180:181]
	s_waitcnt lgkmcnt(0)
	v_pk_add_f32 v[94:95], v[94:95], v[176:177]
	v_pk_add_f32 v[92:93], v[92:93], v[228:229]
	v_pk_add_f32 v[90:91], v[90:91], v[224:225]
	v_pk_add_f32 v[88:89], v[88:89], v[210:211]
	v_pk_add_f32 v[86:87], v[86:87], v[190:191]
	v_pk_add_f32 v[84:85], v[84:85], v[186:187]
	v_pk_add_f32 v[82:83], v[82:83], v[182:183]
	v_pk_add_f32 v[80:81], v[80:81], v[178:179]
	s_nop 0

.Latt_a:
	s_mul_i32 s4, s87, 0x5000
	v_add_u32_e32 v205, s4, v165
	v_add_u32_e32 v206, s5, v192
	ds_read_b64_tr_b16 v[96:97], v205 offset:34816
	ds_read_b64_tr_b16 v[98:99], v205 offset:37376
	ds_read_b64_tr_b16 v[100:101], v205 offset:39936
	ds_read_b64_tr_b16 v[102:103], v205 offset:42496
	ds_read_b64_tr_b16 v[104:105], v205 offset:45056
	ds_read_b64_tr_b16 v[106:107], v205 offset:47616
	ds_read_b64_tr_b16 v[108:109], v205 offset:50176
	ds_read_b64_tr_b16 v[110:111], v205 offset:52736
	ds_read_b64_tr_b16 v[176:177], v205 offset:34880
	ds_read_b64_tr_b16 v[178:179], v205 offset:37440
	ds_read_b64_tr_b16 v[180:181], v205 offset:40000
	ds_read_b64_tr_b16 v[182:183], v205 offset:42560
	ds_read_b64_tr_b16 v[184:185], v205 offset:45120
	ds_read_b64_tr_b16 v[186:187], v205 offset:47680
	s_setprio 1
	s_waitcnt lgkmcnt(10)
	v_mfma_f32_32x32x16_bf16 v[32:47], v[96:99], v[80:83], v[32:47]
	ds_read_b64_tr_b16 v[96:97], v205 offset:50240
	ds_read_b64_tr_b16 v[98:99], v205 offset:52800
	v_mfma_f32_32x32x16_bf16 v[32:47], v[100:103], v[84:87], v[32:47]
	ds_read_b64_tr_b16 v[100:101], v205 offset:34944
	ds_read_b64_tr_b16 v[102:103], v205 offset:37504
	s_waitcnt lgkmcnt(10)
	v_mfma_f32_32x32x16_bf16 v[32:47], v[104:107], v[88:91], v[32:47]
	ds_read_b64_tr_b16 v[104:105], v205 offset:40064
	ds_read_b64_tr_b16 v[106:107], v205 offset:42624
	v_mfma_f32_32x32x16_bf16 v[32:47], v[108:111], v[92:95], v[32:47]
	ds_read_b64_tr_b16 v[108:109], v205 offset:45184
	ds_read_b64_tr_b16 v[110:111], v205 offset:47744
	s_waitcnt lgkmcnt(10)
	v_mfma_f32_32x32x16_bf16 v[16:31], v[176:179], v[80:83], v[16:31]
	ds_read_b64_tr_b16 v[176:177], v205 offset:50304
	ds_read_b64_tr_b16 v[178:179], v205 offset:52864
	v_mfma_f32_32x32x16_bf16 v[16:31], v[180:183], v[84:87], v[16:31]
	ds_read_b64_tr_b16 v[180:181], v205 offset:35008
	ds_read_b64_tr_b16 v[182:183], v205 offset:37568
	s_waitcnt lgkmcnt(10)
	v_mfma_f32_32x32x16_bf16 v[16:31], v[184:187], v[88:91], v[16:31]
	ds_read_b64_tr_b16 v[184:185], v205 offset:40128
	ds_read_b64_tr_b16 v[186:187], v205 offset:42688
	v_mfma_f32_32x32x16_bf16 v[16:31], v[96:99], v[92:95], v[16:31]
	ds_read_b64_tr_b16 v[96:97], v205 offset:45248
	ds_read_b64_tr_b16 v[98:99], v205 offset:47808
	s_waitcnt lgkmcnt(10)
	v_mfma_f32_32x32x16_bf16 v[0:15], v[100:103], v[80:83], v[0:15]
	ds_read_b64_tr_b16 v[100:101], v205 offset:50368
	ds_read_b64_tr_b16 v[102:103], v205 offset:52928
	v_mfma_f32_32x32x16_bf16 v[0:15], v[104:107], v[84:87], v[0:15]
	ds_read_b128 v[210:213], v206 offset:8704
	ds_read_b128 v[104:107], v206 offset:8736
	s_waitcnt lgkmcnt(10)
	v_mfma_f32_32x32x16_bf16 v[0:15], v[108:111], v[88:91], v[0:15]
	ds_read_b128 v[108:111], v206 offset:8768
	ds_read_b128 v[188:191], v206
	v_mfma_f32_32x32x16_bf16 v[0:15], v[176:179], v[92:95], v[0:15]
	ds_read_b128 v[176:179], v206 offset:8800
	ds_read_b128 v[224:227], v206 offset:32
	s_waitcnt lgkmcnt(10)
	v_mfma_f32_32x32x16_bf16 v[48:63], v[180:183], v[80:83], v[48:63]
	ds_read_b128 v[228:231], v206 offset:64
	ds_read_b128 v[248:251], v206 offset:96
	v_mfma_f32_32x32x16_bf16 v[48:63], v[184:187], v[84:87], v[48:63]
	s_waitcnt lgkmcnt(8)
	v_mfma_f32_32x32x16_bf16 v[48:63], v[96:99], v[88:91], v[48:63]
	v_mfma_f32_32x32x16_bf16 v[48:63], v[100:103], v[92:95], v[48:63]
	s_waitcnt lgkmcnt(6)
	v_mfma_f32_32x32x16_bf16 v[80:95], v[210:213], v[112:115], v[64:79]
	v_mfma_f32_32x32x16_bf16 v[80:95], v[104:107], v[116:119], v[80:95]
	s_waitcnt lgkmcnt(3)
	v_mfma_f32_32x32x16_bf16 v[80:95], v[108:111], v[120:123], v[80:95]
	v_mfma_f32_32x32x16_bf16 v[80:95], v[176:179], v[124:127], v[80:95]
	s_waitcnt lgkmcnt(2)
	v_mfma_f32_32x32x16_bf16 v[96:111], v[188:191], v[112:115], v[64:79]
	v_mfma_f32_32x32x16_bf16 v[96:111], v[224:227], v[116:119], v[96:111]
	s_waitcnt lgkmcnt(0)
	v_mfma_f32_32x32x16_bf16 v[96:111], v[228:231], v[120:123], v[96:111]
	v_mfma_f32_32x32x16_bf16 v[96:111], v[248:251], v[124:127], v[96:111]
	s_setprio 0
	s_cmp_gt_i32 s33, 2
	s_cbranch_scc1 .Latt_a_stg
	s_waitcnt lgkmcnt(0)
	v_add_u32_e32 v205, s68, v204
	v_add_u32_e32 v176, 0x17d00, v205
	v_add_u32_e32 v178, 0x17d80, v205
	ds_read2_b32 v[176:177], v176 offset1:1
	ds_read2_b32 v[178:179], v178 offset1:1
	v_add_u32_e32 v180, 0x17d08, v205
	v_add_u32_e32 v182, 0x17d88, v205
	v_add_u32_e32 v184, 0x17d20, v205
	v_add_u32_e32 v186, 0x17da0, v205
	v_add_u32_e32 v188, 0x17d28, v205
	v_add_u32_e32 v190, 0x17da8, v205
	v_add_u32_e32 v206, 0x17d40, v205
	v_add_u32_e32 v210, 0x17dc0, v205
	v_add_u32_e32 v212, 0x17d48, v205
	v_add_u32_e32 v221, 0x17dc8, v205
	ds_read2_b32 v[180:181], v180 offset1:1
	ds_read2_b32 v[182:183], v182 offset1:1
	ds_read2_b32 v[184:185], v184 offset1:1
	ds_read2_b32 v[186:187], v186 offset1:1
	ds_read2_b32 v[188:189], v188 offset1:1
	ds_read2_b32 v[190:191], v190 offset1:1
	ds_read2_b32 v[206:207], v206 offset1:1
	ds_read2_b32 v[210:211], v210 offset1:1
	ds_read2_b32 v[212:213], v212 offset1:1
	ds_read2_b32 v[224:225], v221 offset1:1
	v_add_u32_e32 v221, 0x17d60, v205
	v_add_u32_e32 v223, 0x17de0, v205
	ds_read2_b32 v[226:227], v221 offset1:1
	ds_read2_b32 v[228:229], v223 offset1:1
	v_add_u32_e32 v221, 0x17d68, v205
	v_add_u32_e32 v205, 0x17de8, v205
	ds_read2_b32 v[230:231], v221 offset1:1
	s_waitcnt lgkmcnt(14)
	v_pk_add_f32 v[96:97], v[96:97], v[176:177]
	ds_read2_b32 v[176:177], v205 offset1:1
	s_waitcnt lgkmcnt(3)
	v_pk_add_f32 v[108:109], v[108:109], v[226:227]
	v_pk_add_f32 v[106:107], v[106:107], v[212:213]
	s_waitcnt lgkmcnt(1)
	v_pk_add_f32 v[110:111], v[110:111], v[230:231]
	v_pk_add_f32 v[104:105], v[104:105], v[206:207]
	v_pk_add_f32 v[102:103], v[102:103], v[188:189]
	v_pk_add_f32 v[100:101], v[100:101], v[184:185]
	v_pk_add_f32 v[98:99], v[98:99], v[180:181]
	s_waitcnt lgkmcnt(0)
	v_pk_add_f32 v[94:95], v[94:95], v[176:177]
	v_pk_add_f32 v[92:93], v[92:93], v[228:229]
	v_pk_add_f32 v[90:91], v[90:91], v[224:225]
	v_pk_add_f32 v[88:89], v[88:89], v[210:211]
	v_pk_add_f32 v[86:87], v[86:87], v[190:191]
	v_pk_add_f32 v[84:85], v[84:85], v[186:187]
	v_pk_add_f32 v[82:83], v[82:83], v[182:183]
	v_pk_add_f32 v[80:81], v[80:81], v[178:179]
	s_nop 0
